# grid barrier poll loops: s_sleep 4 -> s_sleep 1 between polls (faster release detection)
# baseline (speedup 1.0000x reference)
.LBB0_91:
	s_and_b32 s16, s20, 0xff
	s_mov_b64 s[14:15], -1
	s_cmp_lg_u32 s16, 0
	s_mov_b64 s[18:19], -1
	s_sleep 1
	s_cbranch_scc1 .LBB0_94
	global_load_dword v3, v1, s[42:43] offset:512 sc1
	s_waitcnt vmcnt(0)
	v_cmp_eq_u32_e32 vcc, 0, v3
	s_cbranch_vccnz .LBB0_96
	s_mov_b64 s[18:19], 0
	s_mov_b64 s[16:17], -1

.LBB0_108:
	s_and_b32 s16, s23, 0xff
	s_cmp_lg_u32 s16, 0
	s_mov_b64 s[18:19], -1
	s_sleep 1
	s_cbranch_scc1 .LBB0_111
	global_load_dword v2, v1, s[8:9] sc1
	s_waitcnt vmcnt(0)
	v_cmp_eq_u32_e32 vcc, 0, v2
	s_cbranch_vccnz .LBB0_113
	s_mov_b64 s[18:19], 0
	s_mov_b64 s[16:17], -1

.LBB0_1590:
	s_and_b32 s14, s18, 0xff
	s_mov_b64 s[12:13], -1
	s_cmp_lg_u32 s14, 0
	s_mov_b64 s[16:17], -1
	s_sleep 1
	s_cbranch_scc1 .LBB0_1593
	global_load_dword v2, v0, s[42:43] offset:512 sc1
	s_waitcnt vmcnt(0)
	v_cmp_eq_u32_e32 vcc, 0, v2
	s_cbranch_vccnz .LBB0_1595
	s_mov_b64 s[16:17], 0
	s_mov_b64 s[14:15], -1

.LBB0_1607:
	s_and_b32 s14, s21, 0xff
	s_cmp_lg_u32 s14, 0
	s_mov_b64 s[16:17], -1
	s_sleep 1
	s_cbranch_scc1 .LBB0_1610
	global_load_dword v1, v0, s[6:7] sc1
	s_waitcnt vmcnt(0)
	v_cmp_eq_u32_e32 vcc, 0, v1
	s_cbranch_vccnz .LBB0_1612
	s_mov_b64 s[16:17], 0
	s_mov_b64 s[14:15], -1
